# GEMM K loops: per-cluster s_setprio flips removed (hardware oldest-first arbitration), otherwise identical to the previous best
# speedup vs baseline: 1.0105x; 1.0105x over previous
.LBB0_169:
	s_add_u32 s20, s22, 0xfff80080
	s_addc_u32 s21, s23, -1
	s_add_i32 s72, 0, 0x10000
	s_cmp_eq_u32 s47, 28
	s_cselect_b32 s67, s17, s21
	s_cselect_b32 s66, vcc_lo, s20
	s_cselect_b32 s21, s15, s97
	s_cselect_b32 s20, vcc_hi, s96
	s_add_i32 s74, 0, 0x14000
	v_add_u32_e32 v70, s72, v195
	v_add_u32_e32 v152, s74, v195
	ds_read_b128 v[48:51], v70
	ds_read_b128 v[52:55], v70 offset:1024
	ds_read_b128 v[66:69], v70 offset:2048
	ds_read_b128 v[70:73], v70 offset:3072
	ds_read_b128 v[176:179], v152
	ds_read_b128 v[198:201], v152 offset:1024
	ds_read_b128 v[202:205], v152 offset:2048
	ds_read_b128 v[206:209], v152 offset:3072
	v_lshl_add_u64 v[180:181], s[22:23], 0, v[172:173]
	s_add_i32 m0, s95, 0xc000
	ds_read_b128 v[210:213], v197
	ds_read_b128 v[214:217], v197 offset:1024
	ds_read_b128 v[218:221], v197 offset:2048
	ds_read_b128 v[222:225], v197 offset:3072
	ds_read_b128 v[226:229], v197 offset:4096
	ds_read_b128 v[230:233], v197 offset:5120
	ds_read_b128 v[234:237], v197 offset:6144
	ds_read_b128 v[238:241], v197 offset:7168
	global_load_lds_dwordx4 v[180:181], off
	v_lshl_add_u64 v[180:181], s[22:23], 0, v[174:175]
	s_add_i32 m0, s95, 0xe000
	s_nop 0
	global_load_lds_dwordx4 v[180:181], off
	s_waitcnt vmcnt(8)
	s_waitcnt lgkmcnt(0)
	s_barrier
	s_waitcnt lgkmcnt(0)
	v_mfma_f32_16x16x32_bf16 v[142:145], v[48:51], v[210:213], v[142:145]
	v_mfma_f32_16x16x32_bf16 v[138:141], v[66:69], v[210:213], v[138:141]
	v_mfma_f32_16x16x32_bf16 v[126:129], v[48:51], v[218:221], v[126:129]
	v_mfma_f32_16x16x32_bf16 v[122:125], v[66:69], v[218:221], v[122:125]
	v_mfma_f32_16x16x32_bf16 v[110:113], v[48:51], v[226:229], v[110:113]
	v_mfma_f32_16x16x32_bf16 v[106:109], v[66:69], v[226:229], v[106:109]
	v_mfma_f32_16x16x32_bf16 v[94:97], v[48:51], v[234:237], v[94:97]
	v_mfma_f32_16x16x32_bf16 v[90:93], v[66:69], v[234:237], v[90:93]
	v_mfma_f32_16x16x32_bf16 v[142:145], v[52:55], v[214:217], v[142:145]
	v_mfma_f32_16x16x32_bf16 v[138:141], v[70:73], v[214:217], v[138:141]
	v_mfma_f32_16x16x32_bf16 v[126:129], v[52:55], v[222:225], v[126:129]
	v_mfma_f32_16x16x32_bf16 v[122:125], v[70:73], v[222:225], v[122:125]
	v_mfma_f32_16x16x32_bf16 v[110:113], v[52:55], v[230:233], v[110:113]
	v_mfma_f32_16x16x32_bf16 v[106:109], v[70:73], v[230:233], v[106:109]
	v_mfma_f32_16x16x32_bf16 v[94:97], v[52:55], v[238:241], v[94:97]
	v_mfma_f32_16x16x32_bf16 v[90:93], v[70:73], v[238:241], v[90:93]
	v_mfma_f32_16x16x32_bf16 v[134:137], v[176:179], v[210:213], v[134:137]
	v_mfma_f32_16x16x32_bf16 v[130:133], v[202:205], v[210:213], v[130:133]
	v_mfma_f32_16x16x32_bf16 v[118:121], v[176:179], v[218:221], v[118:121]
	v_mfma_f32_16x16x32_bf16 v[114:117], v[202:205], v[218:221], v[114:117]
	v_mfma_f32_16x16x32_bf16 v[102:105], v[176:179], v[226:229], v[102:105]
	v_mfma_f32_16x16x32_bf16 v[98:101], v[202:205], v[226:229], v[98:101]
	v_mfma_f32_16x16x32_bf16 v[86:89], v[176:179], v[234:237], v[86:89]
	v_mfma_f32_16x16x32_bf16 v[82:85], v[202:205], v[234:237], v[82:85]
	v_mfma_f32_16x16x32_bf16 v[134:137], v[198:201], v[214:217], v[134:137]
	v_mfma_f32_16x16x32_bf16 v[130:133], v[206:209], v[214:217], v[130:133]
	v_mfma_f32_16x16x32_bf16 v[118:121], v[198:201], v[222:225], v[118:121]
	v_mfma_f32_16x16x32_bf16 v[114:117], v[206:209], v[222:225], v[114:117]
	v_mfma_f32_16x16x32_bf16 v[102:105], v[198:201], v[230:233], v[102:105]
	v_mfma_f32_16x16x32_bf16 v[98:101], v[206:209], v[230:233], v[98:101]
	v_mfma_f32_16x16x32_bf16 v[86:89], v[198:201], v[238:241], v[86:89]
	v_mfma_f32_16x16x32_bf16 v[82:85], v[206:209], v[238:241], v[82:85]
	s_barrier
	s_add_i32 s72, s72, s94
	v_lshl_add_u64 v[180:181], s[20:21], 0, v[154:155]
	s_mov_b32 m0, s72
	ds_read_b128 v[210:213], v197 offset:16384
	ds_read_b128 v[214:217], v197 offset:17408
	ds_read_b128 v[218:221], v197 offset:18432
	ds_read_b128 v[222:225], v197 offset:19456
	ds_read_b128 v[226:229], v197 offset:20480
	ds_read_b128 v[230:233], v197 offset:21504
	ds_read_b128 v[234:237], v197 offset:22528
	ds_read_b128 v[238:241], v197 offset:23552
	global_load_lds_dwordx4 v[180:181], off
	s_add_i32 m0, s72, 0x2000
	s_add_u32 s72, s20, 0x80000
	v_lshl_add_u64 v[242:243], s[20:21], 0, v[158:159]
	s_addc_u32 s73, s21, 0
	s_add_i32 s74, s74, s94
	global_load_lds_dwordx4 v[242:243], off
	v_lshl_add_u64 v[244:245], s[72:73], 0, v[154:155]
	s_mov_b32 m0, s74
	v_lshl_add_u64 v[246:247], s[66:67], 0, v[156:157]
	global_load_lds_dwordx4 v[244:245], off
	v_lshl_add_u64 v[244:245], s[72:73], 0, v[158:159]
	s_add_i32 m0, s74, 0x2000
	s_nop 0
	global_load_lds_dwordx4 v[244:245], off
	v_lshl_add_u64 v[244:245], s[66:67], 0, v[146:147]
	s_mov_b32 m0, s95
	s_nop 0
	global_load_lds_dwordx4 v[244:245], off
	s_mov_b32 m0, s60
	s_nop 0
	global_load_lds_dwordx4 v[246:247], off
	s_waitcnt vmcnt(8)
	s_waitcnt lgkmcnt(0)
	s_barrier
	s_waitcnt lgkmcnt(0)
	v_mfma_f32_16x16x32_bf16 v[78:81], v[48:51], v[210:213], v[78:81]
	v_mfma_f32_16x16x32_bf16 v[74:77], v[66:69], v[210:213], v[74:77]
	v_mfma_f32_16x16x32_bf16 v[44:47], v[48:51], v[218:221], v[44:47]
	v_mfma_f32_16x16x32_bf16 v[40:43], v[66:69], v[218:221], v[40:43]
	v_mfma_f32_16x16x32_bf16 v[28:31], v[48:51], v[226:229], v[28:31]
	v_mfma_f32_16x16x32_bf16 v[24:27], v[66:69], v[226:229], v[24:27]
	v_mfma_f32_16x16x32_bf16 v[12:15], v[48:51], v[234:237], v[12:15]
	v_mfma_f32_16x16x32_bf16 v[8:11], v[66:69], v[234:237], v[8:11]
	v_mfma_f32_16x16x32_bf16 v[78:81], v[52:55], v[214:217], v[78:81]
	v_mfma_f32_16x16x32_bf16 v[74:77], v[70:73], v[214:217], v[74:77]
	v_mfma_f32_16x16x32_bf16 v[44:47], v[52:55], v[222:225], v[44:47]
	v_mfma_f32_16x16x32_bf16 v[40:43], v[70:73], v[222:225], v[40:43]
	v_mfma_f32_16x16x32_bf16 v[28:31], v[52:55], v[230:233], v[28:31]
	v_mfma_f32_16x16x32_bf16 v[24:27], v[70:73], v[230:233], v[24:27]
	v_mfma_f32_16x16x32_bf16 v[12:15], v[52:55], v[238:241], v[12:15]
	v_mfma_f32_16x16x32_bf16 v[8:11], v[70:73], v[238:241], v[8:11]
	v_mfma_f32_16x16x32_bf16 v[36:39], v[176:179], v[218:221], v[36:39]
	v_mfma_f32_16x16x32_bf16 v[32:35], v[202:205], v[218:221], v[32:35]
	v_mfma_f32_16x16x32_bf16 v[20:23], v[176:179], v[226:229], v[20:23]
	v_mfma_f32_16x16x32_bf16 v[16:19], v[202:205], v[226:229], v[16:19]
	v_mfma_f32_16x16x32_bf16 v[4:7], v[176:179], v[234:237], v[4:7]
	v_mfma_f32_16x16x32_bf16 v[0:3], v[202:205], v[234:237], v[0:3]
	v_mfma_f32_16x16x32_bf16 v[48:51], v[176:179], v[210:213], v[60:63]
	v_mfma_f32_16x16x32_bf16 v[52:55], v[202:205], v[210:213], v[56:59]
	v_mfma_f32_16x16x32_bf16 v[36:39], v[198:201], v[222:225], v[36:39]
	v_mfma_f32_16x16x32_bf16 v[32:35], v[206:209], v[222:225], v[32:35]
	v_mfma_f32_16x16x32_bf16 v[20:23], v[198:201], v[230:233], v[20:23]
	v_mfma_f32_16x16x32_bf16 v[16:19], v[206:209], v[230:233], v[16:19]
	v_mfma_f32_16x16x32_bf16 v[4:7], v[198:201], v[238:241], v[4:7]
	v_mfma_f32_16x16x32_bf16 v[0:3], v[206:209], v[238:241], v[0:3]
	v_mfma_f32_16x16x32_bf16 v[48:51], v[198:201], v[214:217], v[48:51]
	v_mfma_f32_16x16x32_bf16 v[52:55], v[206:209], v[214:217], v[52:55]
	s_barrier
	s_add_i32 s72, 0, 0x18000
	s_add_i32 s73, 0, 0x1c000
	v_add_u32_e32 v70, s72, v195
	v_add_u32_e32 v152, s73, v195
	ds_read_b128 v[56:59], v70
	ds_read_b128 v[60:63], v70 offset:1024
	ds_read_b128 v[66:69], v70 offset:2048
	ds_read_b128 v[70:73], v70 offset:3072
	ds_read_b128 v[176:179], v152
	ds_read_b128 v[198:201], v152 offset:1024
	ds_read_b128 v[202:205], v152 offset:2048
	ds_read_b128 v[206:209], v152 offset:3072
	s_add_u32 s66, s66, 0x80000
	s_addc_u32 s67, s67, 0
	s_mov_b32 m0, s61
	v_lshl_add_u64 v[248:249], s[66:67], 0, v[146:147]
	ds_read_b128 v[210:213], v197 offset:32768
	ds_read_b128 v[214:217], v197 offset:33792
	ds_read_b128 v[218:221], v197 offset:34816
	ds_read_b128 v[222:225], v197 offset:35840
	ds_read_b128 v[226:229], v197 offset:36864
	ds_read_b128 v[230:233], v197 offset:37888
	ds_read_b128 v[234:237], v197 offset:38912
	ds_read_b128 v[238:241], v197 offset:39936
	global_load_lds_dwordx4 v[248:249], off
	v_lshl_add_u64 v[248:249], s[66:67], 0, v[156:157]
	s_mov_b32 m0, s26
	s_nop 0
	global_load_lds_dwordx4 v[248:249], off
	s_waitcnt vmcnt(8)
	s_waitcnt lgkmcnt(0)
	s_barrier
	s_waitcnt lgkmcnt(0)
	v_mfma_f32_16x16x32_bf16 v[142:145], v[56:59], v[210:213], v[142:145]
	v_mfma_f32_16x16x32_bf16 v[138:141], v[66:69], v[210:213], v[138:141]
	v_mfma_f32_16x16x32_bf16 v[126:129], v[56:59], v[218:221], v[126:129]
	v_mfma_f32_16x16x32_bf16 v[122:125], v[66:69], v[218:221], v[122:125]
	v_mfma_f32_16x16x32_bf16 v[110:113], v[56:59], v[226:229], v[110:113]
	v_mfma_f32_16x16x32_bf16 v[106:109], v[66:69], v[226:229], v[106:109]
	v_mfma_f32_16x16x32_bf16 v[94:97], v[56:59], v[234:237], v[94:97]
	v_mfma_f32_16x16x32_bf16 v[90:93], v[66:69], v[234:237], v[90:93]
	v_mfma_f32_16x16x32_bf16 v[142:145], v[60:63], v[214:217], v[142:145]
	v_mfma_f32_16x16x32_bf16 v[138:141], v[70:73], v[214:217], v[138:141]
	v_mfma_f32_16x16x32_bf16 v[126:129], v[60:63], v[222:225], v[126:129]
	v_mfma_f32_16x16x32_bf16 v[122:125], v[70:73], v[222:225], v[122:125]
	v_mfma_f32_16x16x32_bf16 v[110:113], v[60:63], v[230:233], v[110:113]
	v_mfma_f32_16x16x32_bf16 v[106:109], v[70:73], v[230:233], v[106:109]
	v_mfma_f32_16x16x32_bf16 v[94:97], v[60:63], v[238:241], v[94:97]
	v_mfma_f32_16x16x32_bf16 v[90:93], v[70:73], v[238:241], v[90:93]
	v_mfma_f32_16x16x32_bf16 v[134:137], v[176:179], v[210:213], v[134:137]
	v_mfma_f32_16x16x32_bf16 v[130:133], v[202:205], v[210:213], v[130:133]
	v_mfma_f32_16x16x32_bf16 v[118:121], v[176:179], v[218:221], v[118:121]
	v_mfma_f32_16x16x32_bf16 v[114:117], v[202:205], v[218:221], v[114:117]
	v_mfma_f32_16x16x32_bf16 v[102:105], v[176:179], v[226:229], v[102:105]
	v_mfma_f32_16x16x32_bf16 v[98:101], v[202:205], v[226:229], v[98:101]
	v_mfma_f32_16x16x32_bf16 v[86:89], v[176:179], v[234:237], v[86:89]
	v_mfma_f32_16x16x32_bf16 v[82:85], v[202:205], v[234:237], v[82:85]
	v_mfma_f32_16x16x32_bf16 v[134:137], v[198:201], v[214:217], v[134:137]
	v_mfma_f32_16x16x32_bf16 v[130:133], v[206:209], v[214:217], v[130:133]
	v_mfma_f32_16x16x32_bf16 v[118:121], v[198:201], v[222:225], v[118:121]
	v_mfma_f32_16x16x32_bf16 v[114:117], v[206:209], v[222:225], v[114:117]
	v_mfma_f32_16x16x32_bf16 v[102:105], v[198:201], v[230:233], v[102:105]
	v_mfma_f32_16x16x32_bf16 v[98:101], v[206:209], v[230:233], v[98:101]
	v_mfma_f32_16x16x32_bf16 v[86:89], v[198:201], v[238:241], v[86:89]
	v_mfma_f32_16x16x32_bf16 v[82:85], v[206:209], v[238:241], v[82:85]
	s_barrier
	s_add_i32 s66, s72, s94
	v_lshl_add_u64 v[180:181], v[180:181], 0, s[30:31]
	s_mov_b32 m0, s66
	ds_read_b128 v[210:213], v197 offset:49152
	ds_read_b128 v[214:217], v197 offset:50176
	ds_read_b128 v[218:221], v197 offset:51200
	ds_read_b128 v[222:225], v197 offset:52224
	ds_read_b128 v[226:229], v197 offset:53248
	ds_read_b128 v[230:233], v197 offset:54272
	ds_read_b128 v[234:237], v197 offset:55296
	ds_read_b128 v[238:241], v197 offset:56320
	global_load_lds_dwordx4 v[180:181], off
	s_add_i32 m0, s66, 0x2000
	s_add_u32 s20, s20, 0x80080
	v_lshl_add_u64 v[180:181], v[242:243], 0, s[30:31]
	s_addc_u32 s21, s21, 0
	s_add_i32 s66, s73, s94
	global_load_lds_dwordx4 v[180:181], off
	v_lshl_add_u64 v[180:181], s[20:21], 0, v[154:155]
	s_mov_b32 m0, s66
	s_nop 0
	global_load_lds_dwordx4 v[180:181], off
	v_lshl_add_u64 v[180:181], s[20:21], 0, v[158:159]
	s_add_i32 m0, s66, 0x2000
	s_nop 0
	global_load_lds_dwordx4 v[180:181], off
	v_lshl_add_u64 v[180:181], v[244:245], 0, s[30:31]
	s_mov_b32 m0, s27
	s_nop 0
	global_load_lds_dwordx4 v[180:181], off
	v_lshl_add_u64 v[180:181], v[246:247], 0, s[30:31]
	s_mov_b32 m0, s28
	s_nop 0
	global_load_lds_dwordx4 v[180:181], off
	s_waitcnt vmcnt(8)
	s_waitcnt lgkmcnt(0)
	s_barrier
	s_waitcnt lgkmcnt(0)
	v_mfma_f32_16x16x32_bf16 v[78:81], v[56:59], v[210:213], v[78:81]
	v_mfma_f32_16x16x32_bf16 v[74:77], v[66:69], v[210:213], v[74:77]
	v_mfma_f32_16x16x32_bf16 v[44:47], v[56:59], v[218:221], v[44:47]
	v_mfma_f32_16x16x32_bf16 v[40:43], v[66:69], v[218:221], v[40:43]
	v_mfma_f32_16x16x32_bf16 v[28:31], v[56:59], v[226:229], v[28:31]
	v_mfma_f32_16x16x32_bf16 v[24:27], v[66:69], v[226:229], v[24:27]
	v_mfma_f32_16x16x32_bf16 v[12:15], v[56:59], v[234:237], v[12:15]
	v_mfma_f32_16x16x32_bf16 v[8:11], v[66:69], v[234:237], v[8:11]
	v_mfma_f32_16x16x32_bf16 v[78:81], v[60:63], v[214:217], v[78:81]
	v_mfma_f32_16x16x32_bf16 v[74:77], v[70:73], v[214:217], v[74:77]
	v_mfma_f32_16x16x32_bf16 v[44:47], v[60:63], v[222:225], v[44:47]
	v_mfma_f32_16x16x32_bf16 v[40:43], v[70:73], v[222:225], v[40:43]
	v_mfma_f32_16x16x32_bf16 v[28:31], v[60:63], v[230:233], v[28:31]
	v_mfma_f32_16x16x32_bf16 v[24:27], v[70:73], v[230:233], v[24:27]
	v_mfma_f32_16x16x32_bf16 v[12:15], v[60:63], v[238:241], v[12:15]
	v_mfma_f32_16x16x32_bf16 v[8:11], v[70:73], v[238:241], v[8:11]
	v_mfma_f32_16x16x32_bf16 v[48:51], v[176:179], v[210:213], v[48:51]
	v_mfma_f32_16x16x32_bf16 v[60:63], v[198:201], v[214:217], v[48:51]
	v_mfma_f32_16x16x32_bf16 v[48:51], v[202:205], v[210:213], v[52:55]
	v_mfma_f32_16x16x32_bf16 v[36:39], v[176:179], v[218:221], v[36:39]
	v_mfma_f32_16x16x32_bf16 v[32:35], v[202:205], v[218:221], v[32:35]
	v_mfma_f32_16x16x32_bf16 v[20:23], v[176:179], v[226:229], v[20:23]
	v_mfma_f32_16x16x32_bf16 v[16:19], v[202:205], v[226:229], v[16:19]
	v_mfma_f32_16x16x32_bf16 v[4:7], v[176:179], v[234:237], v[4:7]
	v_mfma_f32_16x16x32_bf16 v[0:3], v[202:205], v[234:237], v[0:3]
	v_mfma_f32_16x16x32_bf16 v[56:59], v[206:209], v[214:217], v[48:51]
	v_mfma_f32_16x16x32_bf16 v[36:39], v[198:201], v[222:225], v[36:39]
	v_mfma_f32_16x16x32_bf16 v[32:35], v[206:209], v[222:225], v[32:35]
	v_mfma_f32_16x16x32_bf16 v[20:23], v[198:201], v[230:233], v[20:23]
	v_mfma_f32_16x16x32_bf16 v[16:19], v[206:209], v[230:233], v[16:19]
	v_mfma_f32_16x16x32_bf16 v[4:7], v[198:201], v[238:241], v[4:7]
	v_mfma_f32_16x16x32_bf16 v[0:3], v[206:209], v[238:241], v[0:3]
	s_barrier
	s_add_i32 s47, s47, 2
	s_add_u32 s22, s22, 0x100
	s_addc_u32 s23, s23, 0
	s_add_u32 s96, s96, 0x100
	s_addc_u32 s97, s97, 0
	s_cmp_gt_u32 s47, 29
	s_cbranch_scc0 .LBB0_169
	s_and_b64 vcc, exec, s[12:13]
	s_cbranch_vccz .LBB0_172
	s_barrier

.LBB0_189:
	s_add_u32 s18, vcc_lo, 0xfff80080
	s_addc_u32 s19, vcc_hi, -1
	s_add_i32 s72, 0, 0x10000
	s_cmp_eq_u32 s47, 28
	s_cselect_b32 s25, s17, s19
	s_cselect_b32 s24, s23, s18
	v_add_u32_e32 v140, s72, v142
	s_cselect_b32 s19, s15, s97
	s_cselect_b32 s18, s65, s96
	s_add_i32 s74, 0, 0x14000
	ds_read_b128 v[132:135], v140
	ds_read_b128 v[136:139], v140 offset:1024
	ds_read_b128 v[176:179], v140 offset:2048
	ds_read_b128 v[196:199], v140 offset:3072
	v_add_u32_e32 v140, s74, v142
	ds_read_b128 v[200:203], v140
	ds_read_b128 v[204:207], v140 offset:1024
	ds_read_b128 v[208:211], v140 offset:2048
	ds_read_b128 v[212:215], v140 offset:3072
	v_lshl_add_u64 v[140:141], vcc, 0, v[172:173]
	s_add_i32 m0, s55, 0xc000
	ds_read_b128 v[216:219], v144
	ds_read_b128 v[220:223], v144 offset:1024
	ds_read_b128 v[224:227], v144 offset:2048
	ds_read_b128 v[228:231], v144 offset:3072
	ds_read_b128 v[232:235], v144 offset:4096
	ds_read_b128 v[236:239], v144 offset:5120
	ds_read_b128 v[240:243], v144 offset:6144
	ds_read_b128 v[244:247], v144 offset:7168
	global_load_lds_dwordx4 v[140:141], off
	v_lshl_add_u64 v[140:141], vcc, 0, v[174:175]
	s_add_i32 m0, s55, 0xe000
	s_nop 0
	global_load_lds_dwordx4 v[140:141], off
	s_waitcnt vmcnt(8)
	s_waitcnt lgkmcnt(0)
	s_barrier
	s_waitcnt lgkmcnt(0)
	v_mfma_f32_16x16x32_bf16 v[126:129], v[132:135], v[216:219], v[126:129]
	v_mfma_f32_16x16x32_bf16 v[122:125], v[176:179], v[216:219], v[122:125]
	v_mfma_f32_16x16x32_bf16 v[110:113], v[132:135], v[224:227], v[110:113]
	v_mfma_f32_16x16x32_bf16 v[106:109], v[176:179], v[224:227], v[106:109]
	v_mfma_f32_16x16x32_bf16 v[94:97], v[132:135], v[232:235], v[94:97]
	v_mfma_f32_16x16x32_bf16 v[90:93], v[176:179], v[232:235], v[90:93]
	v_mfma_f32_16x16x32_bf16 v[78:81], v[132:135], v[240:243], v[78:81]
	v_mfma_f32_16x16x32_bf16 v[74:77], v[176:179], v[240:243], v[74:77]
	v_mfma_f32_16x16x32_bf16 v[126:129], v[136:139], v[220:223], v[126:129]
	v_mfma_f32_16x16x32_bf16 v[122:125], v[196:199], v[220:223], v[122:125]
	v_mfma_f32_16x16x32_bf16 v[110:113], v[136:139], v[228:231], v[110:113]
	v_mfma_f32_16x16x32_bf16 v[106:109], v[196:199], v[228:231], v[106:109]
	v_mfma_f32_16x16x32_bf16 v[94:97], v[136:139], v[236:239], v[94:97]
	v_mfma_f32_16x16x32_bf16 v[90:93], v[196:199], v[236:239], v[90:93]
	v_mfma_f32_16x16x32_bf16 v[78:81], v[136:139], v[244:247], v[78:81]
	v_mfma_f32_16x16x32_bf16 v[74:77], v[196:199], v[244:247], v[74:77]
	v_mfma_f32_16x16x32_bf16 v[118:121], v[200:203], v[216:219], v[118:121]
	v_mfma_f32_16x16x32_bf16 v[114:117], v[208:211], v[216:219], v[114:117]
	v_mfma_f32_16x16x32_bf16 v[102:105], v[200:203], v[224:227], v[102:105]
	v_mfma_f32_16x16x32_bf16 v[98:101], v[208:211], v[224:227], v[98:101]
	v_mfma_f32_16x16x32_bf16 v[86:89], v[200:203], v[232:235], v[86:89]
	v_mfma_f32_16x16x32_bf16 v[82:85], v[208:211], v[232:235], v[82:85]
	v_mfma_f32_16x16x32_bf16 v[70:73], v[200:203], v[240:243], v[70:73]
	v_mfma_f32_16x16x32_bf16 v[66:69], v[208:211], v[240:243], v[66:69]
	v_mfma_f32_16x16x32_bf16 v[118:121], v[204:207], v[220:223], v[118:121]
	v_mfma_f32_16x16x32_bf16 v[114:117], v[212:215], v[220:223], v[114:117]
	v_mfma_f32_16x16x32_bf16 v[102:105], v[204:207], v[228:231], v[102:105]
	v_mfma_f32_16x16x32_bf16 v[98:101], v[212:215], v[228:231], v[98:101]
	v_mfma_f32_16x16x32_bf16 v[86:89], v[204:207], v[236:239], v[86:89]
	v_mfma_f32_16x16x32_bf16 v[82:85], v[212:215], v[236:239], v[82:85]
	v_mfma_f32_16x16x32_bf16 v[70:73], v[204:207], v[244:247], v[70:73]
	v_mfma_f32_16x16x32_bf16 v[66:69], v[212:215], v[244:247], v[66:69]
	s_barrier
	s_add_i32 s72, s72, s54
	v_lshl_add_u64 v[140:141], s[18:19], 0, v[154:155]
	s_mov_b32 m0, s72
	ds_read_b128 v[216:219], v144 offset:16384
	ds_read_b128 v[220:223], v144 offset:17408
	ds_read_b128 v[224:227], v144 offset:18432
	ds_read_b128 v[228:231], v144 offset:19456
	ds_read_b128 v[232:235], v144 offset:20480
	ds_read_b128 v[236:239], v144 offset:21504
	ds_read_b128 v[240:243], v144 offset:22528
	ds_read_b128 v[244:247], v144 offset:23552
	global_load_lds_dwordx4 v[140:141], off
	s_add_i32 m0, s72, 0x2000
	s_add_u32 s72, s18, 0x80000
	v_lshl_add_u64 v[180:181], s[18:19], 0, v[158:159]
	s_addc_u32 s73, s19, 0
	s_add_i32 s74, s74, s54
	global_load_lds_dwordx4 v[180:181], off
	v_lshl_add_u64 v[248:249], s[72:73], 0, v[154:155]
	s_mov_b32 m0, s74
	v_lshl_add_u64 v[250:251], s[24:25], 0, v[156:157]
	global_load_lds_dwordx4 v[248:249], off
	v_lshl_add_u64 v[248:249], s[72:73], 0, v[158:159]
	s_add_i32 m0, s74, 0x2000
	s_nop 0
	global_load_lds_dwordx4 v[248:249], off
	v_lshl_add_u64 v[248:249], s[24:25], 0, v[146:147]
	s_mov_b32 m0, s55
	s_nop 0
	global_load_lds_dwordx4 v[248:249], off
	s_mov_b32 m0, s60
	s_nop 0
	global_load_lds_dwordx4 v[250:251], off
	s_waitcnt vmcnt(8)
	s_waitcnt lgkmcnt(0)
	s_barrier
	s_waitcnt lgkmcnt(0)
	v_mfma_f32_16x16x32_bf16 v[60:63], v[132:135], v[216:219], v[60:63]
	v_mfma_f32_16x16x32_bf16 v[56:59], v[176:179], v[216:219], v[56:59]
	v_mfma_f32_16x16x32_bf16 v[44:47], v[132:135], v[224:227], v[44:47]
	v_mfma_f32_16x16x32_bf16 v[40:43], v[176:179], v[224:227], v[40:43]
	v_mfma_f32_16x16x32_bf16 v[28:31], v[132:135], v[232:235], v[28:31]
	v_mfma_f32_16x16x32_bf16 v[24:27], v[176:179], v[232:235], v[24:27]
	v_mfma_f32_16x16x32_bf16 v[12:15], v[132:135], v[240:243], v[12:15]
	v_mfma_f32_16x16x32_bf16 v[8:11], v[176:179], v[240:243], v[8:11]
	v_mfma_f32_16x16x32_bf16 v[60:63], v[136:139], v[220:223], v[60:63]
	v_mfma_f32_16x16x32_bf16 v[56:59], v[196:199], v[220:223], v[56:59]
	v_mfma_f32_16x16x32_bf16 v[44:47], v[136:139], v[228:231], v[44:47]
	v_mfma_f32_16x16x32_bf16 v[40:43], v[196:199], v[228:231], v[40:43]
	v_mfma_f32_16x16x32_bf16 v[28:31], v[136:139], v[236:239], v[28:31]
	v_mfma_f32_16x16x32_bf16 v[24:27], v[196:199], v[236:239], v[24:27]
	v_mfma_f32_16x16x32_bf16 v[12:15], v[136:139], v[244:247], v[12:15]
	v_mfma_f32_16x16x32_bf16 v[8:11], v[196:199], v[244:247], v[8:11]
	v_mfma_f32_16x16x32_bf16 v[52:55], v[200:203], v[216:219], v[52:55]
	v_mfma_f32_16x16x32_bf16 v[48:51], v[208:211], v[216:219], v[48:51]
	v_mfma_f32_16x16x32_bf16 v[36:39], v[200:203], v[224:227], v[36:39]
	v_mfma_f32_16x16x32_bf16 v[32:35], v[208:211], v[224:227], v[32:35]
	v_mfma_f32_16x16x32_bf16 v[20:23], v[200:203], v[232:235], v[20:23]
	v_mfma_f32_16x16x32_bf16 v[16:19], v[208:211], v[232:235], v[16:19]
	v_mfma_f32_16x16x32_bf16 v[4:7], v[200:203], v[240:243], v[4:7]
	v_mfma_f32_16x16x32_bf16 v[0:3], v[208:211], v[240:243], v[0:3]
	v_mfma_f32_16x16x32_bf16 v[52:55], v[204:207], v[220:223], v[52:55]
	v_mfma_f32_16x16x32_bf16 v[48:51], v[212:215], v[220:223], v[48:51]
	v_mfma_f32_16x16x32_bf16 v[36:39], v[204:207], v[228:231], v[36:39]
	v_mfma_f32_16x16x32_bf16 v[32:35], v[212:215], v[228:231], v[32:35]
	v_mfma_f32_16x16x32_bf16 v[20:23], v[204:207], v[236:239], v[20:23]
	v_mfma_f32_16x16x32_bf16 v[16:19], v[212:215], v[236:239], v[16:19]
	v_mfma_f32_16x16x32_bf16 v[4:7], v[204:207], v[244:247], v[4:7]
	v_mfma_f32_16x16x32_bf16 v[0:3], v[212:215], v[244:247], v[0:3]
	s_barrier
	s_add_i32 s72, 0, 0x18000
	v_add_u32_e32 v145, s72, v142
	s_add_i32 s73, 0, 0x1c000
	ds_read_b128 v[132:135], v145
	ds_read_b128 v[136:139], v145 offset:1024
	ds_read_b128 v[176:179], v145 offset:2048
	ds_read_b128 v[196:199], v145 offset:3072
	v_add_u32_e32 v145, s73, v142
	ds_read_b128 v[200:203], v145
	ds_read_b128 v[204:207], v145 offset:1024
	ds_read_b128 v[208:211], v145 offset:2048
	ds_read_b128 v[212:215], v145 offset:3072
	s_add_u32 s24, s24, 0x80000
	s_addc_u32 s25, s25, 0
	s_mov_b32 m0, s61
	v_lshl_add_u64 v[152:153], s[24:25], 0, v[146:147]
	ds_read_b128 v[216:219], v144 offset:32768
	ds_read_b128 v[220:223], v144 offset:33792
	ds_read_b128 v[224:227], v144 offset:34816
	ds_read_b128 v[228:231], v144 offset:35840
	ds_read_b128 v[232:235], v144 offset:36864
	ds_read_b128 v[236:239], v144 offset:37888
	ds_read_b128 v[240:243], v144 offset:38912
	ds_read_b128 v[244:247], v144 offset:39936
	global_load_lds_dwordx4 v[152:153], off
	v_lshl_add_u64 v[152:153], s[24:25], 0, v[156:157]
	s_mov_b32 m0, s94
	s_nop 0
	global_load_lds_dwordx4 v[152:153], off
	s_waitcnt vmcnt(8)
	s_waitcnt lgkmcnt(0)
	s_barrier
	s_waitcnt lgkmcnt(0)
	v_mfma_f32_16x16x32_bf16 v[126:129], v[132:135], v[216:219], v[126:129]
	v_mfma_f32_16x16x32_bf16 v[122:125], v[176:179], v[216:219], v[122:125]
	v_mfma_f32_16x16x32_bf16 v[110:113], v[132:135], v[224:227], v[110:113]
	v_mfma_f32_16x16x32_bf16 v[106:109], v[176:179], v[224:227], v[106:109]
	v_mfma_f32_16x16x32_bf16 v[94:97], v[132:135], v[232:235], v[94:97]
	v_mfma_f32_16x16x32_bf16 v[90:93], v[176:179], v[232:235], v[90:93]
	v_mfma_f32_16x16x32_bf16 v[78:81], v[132:135], v[240:243], v[78:81]
	v_mfma_f32_16x16x32_bf16 v[74:77], v[176:179], v[240:243], v[74:77]
	v_mfma_f32_16x16x32_bf16 v[126:129], v[136:139], v[220:223], v[126:129]
	v_mfma_f32_16x16x32_bf16 v[122:125], v[196:199], v[220:223], v[122:125]
	v_mfma_f32_16x16x32_bf16 v[110:113], v[136:139], v[228:231], v[110:113]
	v_mfma_f32_16x16x32_bf16 v[106:109], v[196:199], v[228:231], v[106:109]
	v_mfma_f32_16x16x32_bf16 v[94:97], v[136:139], v[236:239], v[94:97]
	v_mfma_f32_16x16x32_bf16 v[90:93], v[196:199], v[236:239], v[90:93]
	v_mfma_f32_16x16x32_bf16 v[78:81], v[136:139], v[244:247], v[78:81]
	v_mfma_f32_16x16x32_bf16 v[74:77], v[196:199], v[244:247], v[74:77]
	v_mfma_f32_16x16x32_bf16 v[118:121], v[200:203], v[216:219], v[118:121]
	v_mfma_f32_16x16x32_bf16 v[114:117], v[208:211], v[216:219], v[114:117]
	v_mfma_f32_16x16x32_bf16 v[102:105], v[200:203], v[224:227], v[102:105]
	v_mfma_f32_16x16x32_bf16 v[98:101], v[208:211], v[224:227], v[98:101]
	v_mfma_f32_16x16x32_bf16 v[86:89], v[200:203], v[232:235], v[86:89]
	v_mfma_f32_16x16x32_bf16 v[82:85], v[208:211], v[232:235], v[82:85]
	v_mfma_f32_16x16x32_bf16 v[70:73], v[200:203], v[240:243], v[70:73]
	v_mfma_f32_16x16x32_bf16 v[66:69], v[208:211], v[240:243], v[66:69]
	v_mfma_f32_16x16x32_bf16 v[118:121], v[204:207], v[220:223], v[118:121]
	v_mfma_f32_16x16x32_bf16 v[114:117], v[212:215], v[220:223], v[114:117]
	v_mfma_f32_16x16x32_bf16 v[102:105], v[204:207], v[228:231], v[102:105]
	v_mfma_f32_16x16x32_bf16 v[98:101], v[212:215], v[228:231], v[98:101]
	v_mfma_f32_16x16x32_bf16 v[86:89], v[204:207], v[236:239], v[86:89]
	v_mfma_f32_16x16x32_bf16 v[82:85], v[212:215], v[236:239], v[82:85]
	v_mfma_f32_16x16x32_bf16 v[70:73], v[204:207], v[244:247], v[70:73]
	v_mfma_f32_16x16x32_bf16 v[66:69], v[212:215], v[244:247], v[66:69]
	s_barrier
	s_add_i32 s24, s72, s54
	v_lshl_add_u64 v[140:141], v[140:141], 0, s[30:31]
	s_mov_b32 m0, s24
	ds_read_b128 v[216:219], v144 offset:49152
	ds_read_b128 v[220:223], v144 offset:50176
	ds_read_b128 v[224:227], v144 offset:51200
	ds_read_b128 v[228:231], v144 offset:52224
	ds_read_b128 v[232:235], v144 offset:53248
	ds_read_b128 v[236:239], v144 offset:54272
	ds_read_b128 v[240:243], v144 offset:55296
	ds_read_b128 v[244:247], v144 offset:56320
	global_load_lds_dwordx4 v[140:141], off
	s_add_i32 m0, s24, 0x2000
	s_add_u32 s18, s18, 0x80080
	v_lshl_add_u64 v[140:141], v[180:181], 0, s[30:31]
	s_addc_u32 s19, s19, 0
	s_add_i32 s24, s73, s54
	global_load_lds_dwordx4 v[140:141], off
	v_lshl_add_u64 v[140:141], s[18:19], 0, v[154:155]
	s_mov_b32 m0, s24
	s_nop 0
	global_load_lds_dwordx4 v[140:141], off
	v_lshl_add_u64 v[140:141], s[18:19], 0, v[158:159]
	s_add_i32 m0, s24, 0x2000
	s_nop 0
	global_load_lds_dwordx4 v[140:141], off
	v_lshl_add_u64 v[140:141], v[248:249], 0, s[30:31]
	s_mov_b32 m0, s95
	s_nop 0
	global_load_lds_dwordx4 v[140:141], off
	v_lshl_add_u64 v[140:141], v[250:251], 0, s[30:31]
	s_mov_b32 m0, s2
	s_nop 0
	global_load_lds_dwordx4 v[140:141], off
	s_waitcnt vmcnt(8)
	s_waitcnt lgkmcnt(0)
	s_barrier
	s_waitcnt lgkmcnt(0)
	v_mfma_f32_16x16x32_bf16 v[60:63], v[132:135], v[216:219], v[60:63]
	v_mfma_f32_16x16x32_bf16 v[56:59], v[176:179], v[216:219], v[56:59]
	v_mfma_f32_16x16x32_bf16 v[44:47], v[132:135], v[224:227], v[44:47]
	v_mfma_f32_16x16x32_bf16 v[40:43], v[176:179], v[224:227], v[40:43]
	v_mfma_f32_16x16x32_bf16 v[28:31], v[132:135], v[232:235], v[28:31]
	v_mfma_f32_16x16x32_bf16 v[24:27], v[176:179], v[232:235], v[24:27]
	v_mfma_f32_16x16x32_bf16 v[12:15], v[132:135], v[240:243], v[12:15]
	v_mfma_f32_16x16x32_bf16 v[8:11], v[176:179], v[240:243], v[8:11]
	v_mfma_f32_16x16x32_bf16 v[60:63], v[136:139], v[220:223], v[60:63]
	v_mfma_f32_16x16x32_bf16 v[56:59], v[196:199], v[220:223], v[56:59]
	v_mfma_f32_16x16x32_bf16 v[44:47], v[136:139], v[228:231], v[44:47]
	v_mfma_f32_16x16x32_bf16 v[40:43], v[196:199], v[228:231], v[40:43]
	v_mfma_f32_16x16x32_bf16 v[28:31], v[136:139], v[236:239], v[28:31]
	v_mfma_f32_16x16x32_bf16 v[24:27], v[196:199], v[236:239], v[24:27]
	v_mfma_f32_16x16x32_bf16 v[12:15], v[136:139], v[244:247], v[12:15]
	v_mfma_f32_16x16x32_bf16 v[8:11], v[196:199], v[244:247], v[8:11]
	v_mfma_f32_16x16x32_bf16 v[52:55], v[200:203], v[216:219], v[52:55]
	v_mfma_f32_16x16x32_bf16 v[48:51], v[208:211], v[216:219], v[48:51]
	v_mfma_f32_16x16x32_bf16 v[36:39], v[200:203], v[224:227], v[36:39]
	v_mfma_f32_16x16x32_bf16 v[32:35], v[208:211], v[224:227], v[32:35]
	v_mfma_f32_16x16x32_bf16 v[20:23], v[200:203], v[232:235], v[20:23]
	v_mfma_f32_16x16x32_bf16 v[16:19], v[208:211], v[232:235], v[16:19]
	v_mfma_f32_16x16x32_bf16 v[4:7], v[200:203], v[240:243], v[4:7]
	v_mfma_f32_16x16x32_bf16 v[0:3], v[208:211], v[240:243], v[0:3]
	v_mfma_f32_16x16x32_bf16 v[52:55], v[204:207], v[220:223], v[52:55]
	v_mfma_f32_16x16x32_bf16 v[48:51], v[212:215], v[220:223], v[48:51]
	v_mfma_f32_16x16x32_bf16 v[36:39], v[204:207], v[228:231], v[36:39]
	v_mfma_f32_16x16x32_bf16 v[32:35], v[212:215], v[228:231], v[32:35]
	v_mfma_f32_16x16x32_bf16 v[20:23], v[204:207], v[236:239], v[20:23]
	v_mfma_f32_16x16x32_bf16 v[16:19], v[212:215], v[236:239], v[16:19]
	v_mfma_f32_16x16x32_bf16 v[4:7], v[204:207], v[244:247], v[4:7]
	v_mfma_f32_16x16x32_bf16 v[0:3], v[212:215], v[244:247], v[0:3]
	s_barrier
	s_add_i32 s47, s47, 2
	s_add_u32 vcc_lo, vcc_lo, 0x100
	s_addc_u32 vcc_hi, vcc_hi, 0
	s_add_u32 s96, s96, 0x100
	s_addc_u32 s97, s97, 0
	s_cmp_gt_u32 s47, 29
	s_cbranch_scc0 .LBB0_189
	s_and_b64 vcc, exec, s[10:11]
	s_cbranch_vccz .LBB0_192
	s_barrier

.LBB0_329:
	s_add_u32 s18, s16, 0xfff80080
	s_addc_u32 s19, s17, -1
	s_add_i32 s27, 0, 0x10000
	s_cmp_eq_u32 s26, 28
	s_cselect_b32 s21, s0, s19
	s_cselect_b32 s20, s2, s18
	v_add_u32_e32 v64, s27, v165
	s_cselect_b32 s19, s3, s11
	s_cselect_b32 s18, s5, s9
	s_add_i32 s47, 0, 0x14000
	ds_read_b128 v[144:147], v64
	ds_read_b128 v[154:157], v64 offset:1024
	ds_read_b128 v[158:161], v64 offset:2048
	ds_read_b128 v[170:173], v64 offset:3072
	v_add_u32_e32 v64, s27, v165
	ds_read_b128 v[174:177], v64 offset:4096
	ds_read_b128 v[178:181], v64 offset:5120
	ds_read_b128 v[192:195], v64 offset:6144
	ds_read_b128 v[196:199], v64 offset:7168
	v_lshl_add_u64 v[162:163], s[16:17], 0, v[140:141]
	s_add_i32 m0, s53, 0xc000
	ds_read_b128 v[200:203], v169
	ds_read_b128 v[204:207], v169 offset:1024
	ds_read_b128 v[208:211], v169 offset:2048
	ds_read_b128 v[212:215], v169 offset:3072
	ds_read_b128 v[216:219], v169 offset:4096
	ds_read_b128 v[220:223], v169 offset:5120
	ds_read_b128 v[224:227], v169 offset:6144
	ds_read_b128 v[228:231], v169 offset:7168
	global_load_lds_dwordx4 v[162:163], off
	v_lshl_add_u64 v[162:163], s[16:17], 0, v[142:143]
	s_add_i32 m0, s53, 0xe000
	s_nop 0
	global_load_lds_dwordx4 v[162:163], off
	s_waitcnt vmcnt(8)
	s_waitcnt lgkmcnt(0)
	s_barrier
	s_waitcnt lgkmcnt(0)
	v_mfma_f32_16x16x32_bf16 v[60:63], v[144:147], v[200:203], v[60:63]
	v_mfma_f32_16x16x32_bf16 v[56:59], v[158:161], v[200:203], v[56:59]
	v_mfma_f32_16x16x32_bf16 v[52:55], v[144:147], v[208:211], v[52:55]
	v_mfma_f32_16x16x32_bf16 v[48:51], v[158:161], v[208:211], v[48:51]
	v_mfma_f32_16x16x32_bf16 v[44:47], v[144:147], v[216:219], v[44:47]
	v_mfma_f32_16x16x32_bf16 v[40:43], v[158:161], v[216:219], v[40:43]
	v_mfma_f32_16x16x32_bf16 v[36:39], v[144:147], v[224:227], v[36:39]
	v_mfma_f32_16x16x32_bf16 v[32:35], v[158:161], v[224:227], v[32:35]
	v_mfma_f32_16x16x32_bf16 v[60:63], v[154:157], v[204:207], v[60:63]
	v_mfma_f32_16x16x32_bf16 v[56:59], v[170:173], v[204:207], v[56:59]
	v_mfma_f32_16x16x32_bf16 v[52:55], v[154:157], v[212:215], v[52:55]
	v_mfma_f32_16x16x32_bf16 v[48:51], v[170:173], v[212:215], v[48:51]
	v_mfma_f32_16x16x32_bf16 v[44:47], v[154:157], v[220:223], v[44:47]
	v_mfma_f32_16x16x32_bf16 v[40:43], v[170:173], v[220:223], v[40:43]
	v_mfma_f32_16x16x32_bf16 v[36:39], v[154:157], v[228:231], v[36:39]
	v_mfma_f32_16x16x32_bf16 v[32:35], v[170:173], v[228:231], v[32:35]
	v_mfma_f32_16x16x32_bf16 v[126:129], v[174:177], v[200:203], v[126:129]
	v_mfma_f32_16x16x32_bf16 v[122:125], v[192:195], v[200:203], v[122:125]
	v_mfma_f32_16x16x32_bf16 v[118:121], v[174:177], v[208:211], v[118:121]
	v_mfma_f32_16x16x32_bf16 v[114:117], v[192:195], v[208:211], v[114:117]
	v_mfma_f32_16x16x32_bf16 v[110:113], v[174:177], v[216:219], v[110:113]
	v_mfma_f32_16x16x32_bf16 v[106:109], v[192:195], v[216:219], v[106:109]
	v_mfma_f32_16x16x32_bf16 v[102:105], v[174:177], v[224:227], v[102:105]
	v_mfma_f32_16x16x32_bf16 v[98:101], v[192:195], v[224:227], v[98:101]
	v_mfma_f32_16x16x32_bf16 v[126:129], v[178:181], v[204:207], v[126:129]
	v_mfma_f32_16x16x32_bf16 v[122:125], v[196:199], v[204:207], v[122:125]
	v_mfma_f32_16x16x32_bf16 v[118:121], v[178:181], v[212:215], v[118:121]
	v_mfma_f32_16x16x32_bf16 v[114:117], v[196:199], v[212:215], v[114:117]
	v_mfma_f32_16x16x32_bf16 v[110:113], v[178:181], v[220:223], v[110:113]
	v_mfma_f32_16x16x32_bf16 v[106:109], v[196:199], v[220:223], v[106:109]
	v_mfma_f32_16x16x32_bf16 v[102:105], v[178:181], v[228:231], v[102:105]
	v_mfma_f32_16x16x32_bf16 v[98:101], v[196:199], v[228:231], v[98:101]
	s_barrier
	s_add_i32 s27, s27, s54
	v_lshl_add_u64 v[162:163], s[18:19], 0, v[132:133]
	s_mov_b32 m0, s27
	ds_read_b128 v[200:203], v169 offset:16384
	ds_read_b128 v[204:207], v169 offset:17408
	ds_read_b128 v[208:211], v169 offset:18432
	ds_read_b128 v[212:215], v169 offset:19456
	ds_read_b128 v[216:219], v169 offset:20480
	ds_read_b128 v[220:223], v169 offset:21504
	ds_read_b128 v[224:227], v169 offset:22528
	ds_read_b128 v[228:231], v169 offset:23552
	global_load_lds_dwordx4 v[162:163], off
	s_add_i32 m0, s27, 0x2000
	s_add_u32 s28, s18, 0x80000
	v_lshl_add_u64 v[232:233], s[18:19], 0, v[136:137]
	s_addc_u32 s29, s19, 0
	s_add_i32 s27, s47, s54
	global_load_lds_dwordx4 v[232:233], off
	v_lshl_add_u64 v[234:235], s[28:29], 0, v[132:133]
	s_mov_b32 m0, s27
	v_lshl_add_u64 v[236:237], s[20:21], 0, v[134:135]
	global_load_lds_dwordx4 v[234:235], off
	v_lshl_add_u64 v[234:235], s[28:29], 0, v[136:137]
	s_add_i32 m0, s27, 0x2000
	s_nop 0
	global_load_lds_dwordx4 v[234:235], off
	v_lshl_add_u64 v[234:235], s[20:21], 0, v[130:131]
	s_mov_b32 m0, s53
	s_nop 0
	global_load_lds_dwordx4 v[234:235], off
	s_mov_b32 m0, s55
	s_nop 0
	global_load_lds_dwordx4 v[236:237], off
	s_waitcnt vmcnt(8)
	s_waitcnt lgkmcnt(0)
	s_barrier
	s_waitcnt lgkmcnt(0)
	v_mfma_f32_16x16x32_bf16 v[28:31], v[144:147], v[200:203], v[28:31]
	v_mfma_f32_16x16x32_bf16 v[24:27], v[158:161], v[200:203], v[24:27]
	v_mfma_f32_16x16x32_bf16 v[20:23], v[144:147], v[208:211], v[20:23]
	v_mfma_f32_16x16x32_bf16 v[16:19], v[158:161], v[208:211], v[16:19]
	v_mfma_f32_16x16x32_bf16 v[12:15], v[144:147], v[216:219], v[12:15]
	v_mfma_f32_16x16x32_bf16 v[8:11], v[158:161], v[216:219], v[8:11]
	v_mfma_f32_16x16x32_bf16 v[4:7], v[144:147], v[224:227], v[4:7]
	v_mfma_f32_16x16x32_bf16 v[0:3], v[158:161], v[224:227], v[0:3]
	v_mfma_f32_16x16x32_bf16 v[28:31], v[154:157], v[204:207], v[28:31]
	v_mfma_f32_16x16x32_bf16 v[24:27], v[170:173], v[204:207], v[24:27]
	v_mfma_f32_16x16x32_bf16 v[20:23], v[154:157], v[212:215], v[20:23]
	v_mfma_f32_16x16x32_bf16 v[16:19], v[170:173], v[212:215], v[16:19]
	v_mfma_f32_16x16x32_bf16 v[12:15], v[154:157], v[220:223], v[12:15]
	v_mfma_f32_16x16x32_bf16 v[8:11], v[170:173], v[220:223], v[8:11]
	v_mfma_f32_16x16x32_bf16 v[4:7], v[154:157], v[228:231], v[4:7]
	v_mfma_f32_16x16x32_bf16 v[0:3], v[170:173], v[228:231], v[0:3]
	v_mfma_f32_16x16x32_bf16 v[94:97], v[174:177], v[200:203], v[94:97]
	v_mfma_f32_16x16x32_bf16 v[90:93], v[192:195], v[200:203], v[90:93]
	v_mfma_f32_16x16x32_bf16 v[86:89], v[174:177], v[208:211], v[86:89]
	v_mfma_f32_16x16x32_bf16 v[82:85], v[192:195], v[208:211], v[82:85]
	v_mfma_f32_16x16x32_bf16 v[78:81], v[174:177], v[216:219], v[78:81]
	v_mfma_f32_16x16x32_bf16 v[74:77], v[192:195], v[216:219], v[74:77]
	v_mfma_f32_16x16x32_bf16 v[70:73], v[174:177], v[224:227], v[70:73]
	v_mfma_f32_16x16x32_bf16 v[66:69], v[192:195], v[224:227], v[66:69]
	v_mfma_f32_16x16x32_bf16 v[94:97], v[178:181], v[204:207], v[94:97]
	v_mfma_f32_16x16x32_bf16 v[90:93], v[196:199], v[204:207], v[90:93]
	v_mfma_f32_16x16x32_bf16 v[86:89], v[178:181], v[212:215], v[86:89]
	v_mfma_f32_16x16x32_bf16 v[82:85], v[196:199], v[212:215], v[82:85]
	v_mfma_f32_16x16x32_bf16 v[78:81], v[178:181], v[220:223], v[78:81]
	v_mfma_f32_16x16x32_bf16 v[74:77], v[196:199], v[220:223], v[74:77]
	v_mfma_f32_16x16x32_bf16 v[70:73], v[178:181], v[228:231], v[70:73]
	v_mfma_f32_16x16x32_bf16 v[66:69], v[196:199], v[228:231], v[66:69]
	s_barrier
	s_add_i32 s27, 0, 0x18000
	v_add_u32_e32 v64, s27, v165
	s_add_i32 s28, 0, 0x1c000
	ds_read_b128 v[144:147], v64
	ds_read_b128 v[154:157], v64 offset:1024
	ds_read_b128 v[158:161], v64 offset:2048
	ds_read_b128 v[170:173], v64 offset:3072
	v_add_u32_e32 v64, s27, v165
	ds_read_b128 v[174:177], v64 offset:4096
	ds_read_b128 v[178:181], v64 offset:5120
	ds_read_b128 v[192:195], v64 offset:6144
	ds_read_b128 v[196:199], v64 offset:7168
	s_add_u32 s20, s20, 0x80000
	s_addc_u32 s21, s21, 0
	s_mov_b32 m0, s6
	v_lshl_add_u64 v[238:239], s[20:21], 0, v[130:131]
	ds_read_b128 v[200:203], v169 offset:32768
	ds_read_b128 v[204:207], v169 offset:33792
	ds_read_b128 v[208:211], v169 offset:34816
	ds_read_b128 v[212:215], v169 offset:35840
	ds_read_b128 v[216:219], v169 offset:36864
	ds_read_b128 v[220:223], v169 offset:37888
	ds_read_b128 v[224:227], v169 offset:38912
	ds_read_b128 v[228:231], v169 offset:39936
	global_load_lds_dwordx4 v[238:239], off
	v_lshl_add_u64 v[238:239], s[20:21], 0, v[134:135]
	s_mov_b32 m0, s7
	s_nop 0
	global_load_lds_dwordx4 v[238:239], off
	s_waitcnt vmcnt(8)
	s_waitcnt lgkmcnt(0)
	s_barrier
	s_waitcnt lgkmcnt(0)
	v_mfma_f32_16x16x32_bf16 v[60:63], v[144:147], v[200:203], v[60:63]
	v_mfma_f32_16x16x32_bf16 v[56:59], v[158:161], v[200:203], v[56:59]
	v_mfma_f32_16x16x32_bf16 v[52:55], v[144:147], v[208:211], v[52:55]
	v_mfma_f32_16x16x32_bf16 v[48:51], v[158:161], v[208:211], v[48:51]
	v_mfma_f32_16x16x32_bf16 v[44:47], v[144:147], v[216:219], v[44:47]
	v_mfma_f32_16x16x32_bf16 v[40:43], v[158:161], v[216:219], v[40:43]
	v_mfma_f32_16x16x32_bf16 v[36:39], v[144:147], v[224:227], v[36:39]
	v_mfma_f32_16x16x32_bf16 v[32:35], v[158:161], v[224:227], v[32:35]
	v_mfma_f32_16x16x32_bf16 v[60:63], v[154:157], v[204:207], v[60:63]
	v_mfma_f32_16x16x32_bf16 v[56:59], v[170:173], v[204:207], v[56:59]
	v_mfma_f32_16x16x32_bf16 v[52:55], v[154:157], v[212:215], v[52:55]
	v_mfma_f32_16x16x32_bf16 v[48:51], v[170:173], v[212:215], v[48:51]
	v_mfma_f32_16x16x32_bf16 v[44:47], v[154:157], v[220:223], v[44:47]
	v_mfma_f32_16x16x32_bf16 v[40:43], v[170:173], v[220:223], v[40:43]
	v_mfma_f32_16x16x32_bf16 v[36:39], v[154:157], v[228:231], v[36:39]
	v_mfma_f32_16x16x32_bf16 v[32:35], v[170:173], v[228:231], v[32:35]
	v_mfma_f32_16x16x32_bf16 v[126:129], v[174:177], v[200:203], v[126:129]
	v_mfma_f32_16x16x32_bf16 v[122:125], v[192:195], v[200:203], v[122:125]
	v_mfma_f32_16x16x32_bf16 v[118:121], v[174:177], v[208:211], v[118:121]
	v_mfma_f32_16x16x32_bf16 v[114:117], v[192:195], v[208:211], v[114:117]
	v_mfma_f32_16x16x32_bf16 v[110:113], v[174:177], v[216:219], v[110:113]
	v_mfma_f32_16x16x32_bf16 v[106:109], v[192:195], v[216:219], v[106:109]
	v_mfma_f32_16x16x32_bf16 v[102:105], v[174:177], v[224:227], v[102:105]
	v_mfma_f32_16x16x32_bf16 v[98:101], v[192:195], v[224:227], v[98:101]
	v_mfma_f32_16x16x32_bf16 v[126:129], v[178:181], v[204:207], v[126:129]
	v_mfma_f32_16x16x32_bf16 v[122:125], v[196:199], v[204:207], v[122:125]
	v_mfma_f32_16x16x32_bf16 v[118:121], v[178:181], v[212:215], v[118:121]
	v_mfma_f32_16x16x32_bf16 v[114:117], v[196:199], v[212:215], v[114:117]
	v_mfma_f32_16x16x32_bf16 v[110:113], v[178:181], v[220:223], v[110:113]
	v_mfma_f32_16x16x32_bf16 v[106:109], v[196:199], v[220:223], v[106:109]
	v_mfma_f32_16x16x32_bf16 v[102:105], v[178:181], v[228:231], v[102:105]
	v_mfma_f32_16x16x32_bf16 v[98:101], v[196:199], v[228:231], v[98:101]
	s_barrier
	s_add_i32 s20, s27, s54
	v_lshl_add_u64 v[162:163], v[162:163], 0, s[30:31]
	s_mov_b32 m0, s20
	ds_read_b128 v[200:203], v169 offset:49152
	ds_read_b128 v[204:207], v169 offset:50176
	ds_read_b128 v[208:211], v169 offset:51200
	ds_read_b128 v[212:215], v169 offset:52224
	ds_read_b128 v[216:219], v169 offset:53248
	ds_read_b128 v[220:223], v169 offset:54272
	ds_read_b128 v[224:227], v169 offset:55296
	ds_read_b128 v[228:231], v169 offset:56320
	global_load_lds_dwordx4 v[162:163], off
	s_add_i32 m0, s20, 0x2000
	s_add_u32 s18, s18, 0x80080
	v_lshl_add_u64 v[162:163], v[232:233], 0, s[30:31]
	s_addc_u32 s19, s19, 0
	s_add_i32 s20, s28, s54
	global_load_lds_dwordx4 v[162:163], off
	v_lshl_add_u64 v[162:163], s[18:19], 0, v[132:133]
	s_mov_b32 m0, s20
	s_nop 0
	global_load_lds_dwordx4 v[162:163], off
	v_lshl_add_u64 v[162:163], s[18:19], 0, v[136:137]
	s_add_i32 m0, s20, 0x2000
	s_nop 0
	global_load_lds_dwordx4 v[162:163], off
	v_lshl_add_u64 v[162:163], v[234:235], 0, s[30:31]
	s_mov_b32 m0, s59
	s_nop 0
	global_load_lds_dwordx4 v[162:163], off
	v_lshl_add_u64 v[162:163], v[236:237], 0, s[30:31]
	s_mov_b32 m0, s58
	s_nop 0
	global_load_lds_dwordx4 v[162:163], off
	s_waitcnt vmcnt(8)
	s_waitcnt lgkmcnt(0)
	s_barrier
	s_waitcnt lgkmcnt(0)
	v_mfma_f32_16x16x32_bf16 v[28:31], v[144:147], v[200:203], v[28:31]
	v_mfma_f32_16x16x32_bf16 v[24:27], v[158:161], v[200:203], v[24:27]
	v_mfma_f32_16x16x32_bf16 v[20:23], v[144:147], v[208:211], v[20:23]
	v_mfma_f32_16x16x32_bf16 v[16:19], v[158:161], v[208:211], v[16:19]
	v_mfma_f32_16x16x32_bf16 v[12:15], v[144:147], v[216:219], v[12:15]
	v_mfma_f32_16x16x32_bf16 v[8:11], v[158:161], v[216:219], v[8:11]
	v_mfma_f32_16x16x32_bf16 v[4:7], v[144:147], v[224:227], v[4:7]
	v_mfma_f32_16x16x32_bf16 v[0:3], v[158:161], v[224:227], v[0:3]
	v_mfma_f32_16x16x32_bf16 v[28:31], v[154:157], v[204:207], v[28:31]
	v_mfma_f32_16x16x32_bf16 v[24:27], v[170:173], v[204:207], v[24:27]
	v_mfma_f32_16x16x32_bf16 v[20:23], v[154:157], v[212:215], v[20:23]
	v_mfma_f32_16x16x32_bf16 v[16:19], v[170:173], v[212:215], v[16:19]
	v_mfma_f32_16x16x32_bf16 v[12:15], v[154:157], v[220:223], v[12:15]
	v_mfma_f32_16x16x32_bf16 v[8:11], v[170:173], v[220:223], v[8:11]
	v_mfma_f32_16x16x32_bf16 v[4:7], v[154:157], v[228:231], v[4:7]
	v_mfma_f32_16x16x32_bf16 v[0:3], v[170:173], v[228:231], v[0:3]
	v_mfma_f32_16x16x32_bf16 v[94:97], v[174:177], v[200:203], v[94:97]
	v_mfma_f32_16x16x32_bf16 v[90:93], v[192:195], v[200:203], v[90:93]
	v_mfma_f32_16x16x32_bf16 v[86:89], v[174:177], v[208:211], v[86:89]
	v_mfma_f32_16x16x32_bf16 v[82:85], v[192:195], v[208:211], v[82:85]
	v_mfma_f32_16x16x32_bf16 v[78:81], v[174:177], v[216:219], v[78:81]
	v_mfma_f32_16x16x32_bf16 v[74:77], v[192:195], v[216:219], v[74:77]
	v_mfma_f32_16x16x32_bf16 v[70:73], v[174:177], v[224:227], v[70:73]
	v_mfma_f32_16x16x32_bf16 v[66:69], v[192:195], v[224:227], v[66:69]
	v_mfma_f32_16x16x32_bf16 v[94:97], v[178:181], v[204:207], v[94:97]
	v_mfma_f32_16x16x32_bf16 v[90:93], v[196:199], v[204:207], v[90:93]
	v_mfma_f32_16x16x32_bf16 v[86:89], v[178:181], v[212:215], v[86:89]
	v_mfma_f32_16x16x32_bf16 v[82:85], v[196:199], v[212:215], v[82:85]
	v_mfma_f32_16x16x32_bf16 v[78:81], v[178:181], v[220:223], v[78:81]
	v_mfma_f32_16x16x32_bf16 v[74:77], v[196:199], v[220:223], v[74:77]
	v_mfma_f32_16x16x32_bf16 v[70:73], v[178:181], v[228:231], v[70:73]
	v_mfma_f32_16x16x32_bf16 v[66:69], v[196:199], v[228:231], v[66:69]
	s_barrier
	s_add_i32 s26, s26, 2
	s_add_u32 s16, s16, 0x100
	s_addc_u32 s17, s17, 0
	s_add_u32 s9, s9, 0x100
	s_addc_u32 s11, s11, 0
	s_cmp_gt_u32 s26, 29
	s_cbranch_scc0 .LBB0_329
	s_and_b64 vcc, exec, s[74:75]
	s_cbranch_vccnz .LBB0_333
	s_cmpk_lg_i32 s52, 0x50
	s_mov_b64 s[16:17], -1
	s_movk_i32 s28, 0x101
	s_cbranch_scc1 .LBB0_334

.LBB0_404:
	s_add_u32 s22, s20, 0xfff80080
	s_addc_u32 s23, s21, -1
	s_add_i32 s65, 0, 0x10000
	s_cmp_eq_u32 s47, 28
	s_cselect_b32 s25, s15, s23
	s_cselect_b32 s24, s59, s22
	v_add_u32_e32 v152, s65, v141
	s_cselect_b32 s23, s13, s64
	s_cselect_b32 s22, s60, s61
	s_add_i32 s72, 0, 0x14000
	ds_read_b128 v[144:147], v152
	ds_read_b128 v[154:157], v152 offset:1024
	ds_read_b128 v[158:161], v152 offset:2048
	ds_read_b128 v[162:165], v152 offset:3072
	v_add_u32_e32 v152, s65, v141
	ds_read_b128 v[166:169], v152 offset:4096
	ds_read_b128 v[170:173], v152 offset:5120
	ds_read_b128 v[174:177], v152 offset:6144
	ds_read_b128 v[178:181], v152 offset:7168
	v_lshl_add_u64 v[152:153], s[20:21], 0, v[136:137]
	s_add_i32 m0, s52, 0xc000
	ds_read_b128 v[192:195], v143
	ds_read_b128 v[196:199], v143 offset:1024
	ds_read_b128 v[200:203], v143 offset:2048
	ds_read_b128 v[204:207], v143 offset:3072
	ds_read_b128 v[208:211], v143 offset:4096
	ds_read_b128 v[212:215], v143 offset:5120
	ds_read_b128 v[216:219], v143 offset:6144
	ds_read_b128 v[220:223], v143 offset:7168
	global_load_lds_dwordx4 v[152:153], off
	v_lshl_add_u64 v[152:153], s[20:21], 0, v[138:139]
	s_add_i32 m0, s52, 0xe000
	s_nop 0
	global_load_lds_dwordx4 v[152:153], off
	s_waitcnt vmcnt(8)
	s_waitcnt lgkmcnt(0)
	s_barrier
	s_waitcnt lgkmcnt(0)
	v_mfma_f32_16x16x32_bf16 v[126:129], v[144:147], v[192:195], v[126:129]
	v_mfma_f32_16x16x32_bf16 v[122:125], v[158:161], v[192:195], v[122:125]
	v_mfma_f32_16x16x32_bf16 v[118:121], v[144:147], v[200:203], v[118:121]
	v_mfma_f32_16x16x32_bf16 v[114:117], v[158:161], v[200:203], v[114:117]
	v_mfma_f32_16x16x32_bf16 v[102:105], v[144:147], v[208:211], v[102:105]
	v_mfma_f32_16x16x32_bf16 v[98:101], v[158:161], v[208:211], v[98:101]
	v_mfma_f32_16x16x32_bf16 v[86:89], v[144:147], v[216:219], v[86:89]
	v_mfma_f32_16x16x32_bf16 v[82:85], v[158:161], v[216:219], v[82:85]
	v_mfma_f32_16x16x32_bf16 v[126:129], v[154:157], v[196:199], v[126:129]
	v_mfma_f32_16x16x32_bf16 v[122:125], v[162:165], v[196:199], v[122:125]
	v_mfma_f32_16x16x32_bf16 v[118:121], v[154:157], v[204:207], v[118:121]
	v_mfma_f32_16x16x32_bf16 v[114:117], v[162:165], v[204:207], v[114:117]
	v_mfma_f32_16x16x32_bf16 v[102:105], v[154:157], v[212:215], v[102:105]
	v_mfma_f32_16x16x32_bf16 v[98:101], v[162:165], v[212:215], v[98:101]
	v_mfma_f32_16x16x32_bf16 v[86:89], v[154:157], v[220:223], v[86:89]
	v_mfma_f32_16x16x32_bf16 v[82:85], v[162:165], v[220:223], v[82:85]
	v_mfma_f32_16x16x32_bf16 v[110:113], v[166:169], v[192:195], v[110:113]
	v_mfma_f32_16x16x32_bf16 v[106:109], v[174:177], v[192:195], v[106:109]
	v_mfma_f32_16x16x32_bf16 v[94:97], v[166:169], v[200:203], v[94:97]
	v_mfma_f32_16x16x32_bf16 v[90:93], v[174:177], v[200:203], v[90:93]
	v_mfma_f32_16x16x32_bf16 v[78:81], v[166:169], v[208:211], v[78:81]
	v_mfma_f32_16x16x32_bf16 v[74:77], v[174:177], v[208:211], v[74:77]
	v_mfma_f32_16x16x32_bf16 v[70:73], v[166:169], v[216:219], v[70:73]
	v_mfma_f32_16x16x32_bf16 v[66:69], v[174:177], v[216:219], v[66:69]
	v_mfma_f32_16x16x32_bf16 v[110:113], v[170:173], v[196:199], v[110:113]
	v_mfma_f32_16x16x32_bf16 v[106:109], v[178:181], v[196:199], v[106:109]
	v_mfma_f32_16x16x32_bf16 v[94:97], v[170:173], v[204:207], v[94:97]
	v_mfma_f32_16x16x32_bf16 v[90:93], v[178:181], v[204:207], v[90:93]
	v_mfma_f32_16x16x32_bf16 v[78:81], v[170:173], v[212:215], v[78:81]
	v_mfma_f32_16x16x32_bf16 v[74:77], v[178:181], v[212:215], v[74:77]
	v_mfma_f32_16x16x32_bf16 v[70:73], v[170:173], v[220:223], v[70:73]
	v_mfma_f32_16x16x32_bf16 v[66:69], v[178:181], v[220:223], v[66:69]
	s_barrier
	s_add_i32 s65, s65, s29
	v_lshl_add_u64 v[152:153], s[22:23], 0, v[64:65]
	s_mov_b32 m0, s65
	ds_read_b128 v[192:195], v143 offset:16384
	ds_read_b128 v[196:199], v143 offset:17408
	ds_read_b128 v[200:203], v143 offset:18432
	ds_read_b128 v[204:207], v143 offset:19456
	ds_read_b128 v[208:211], v143 offset:20480
	ds_read_b128 v[212:215], v143 offset:21504
	ds_read_b128 v[216:219], v143 offset:22528
	ds_read_b128 v[220:223], v143 offset:23552
	global_load_lds_dwordx4 v[152:153], off
	s_add_i32 m0, s65, 0x2000
	s_add_u32 s66, s22, 0x80000
	v_lshl_add_u64 v[224:225], s[22:23], 0, v[134:135]
	s_addc_u32 s67, s23, 0
	s_add_i32 s65, s72, s29
	global_load_lds_dwordx4 v[224:225], off
	v_lshl_add_u64 v[226:227], s[66:67], 0, v[64:65]
	s_mov_b32 m0, s65
	v_lshl_add_u64 v[228:229], s[24:25], 0, v[132:133]
	global_load_lds_dwordx4 v[226:227], off
	v_lshl_add_u64 v[226:227], s[66:67], 0, v[134:135]
	s_add_i32 m0, s65, 0x2000
	s_nop 0
	global_load_lds_dwordx4 v[226:227], off
	v_lshl_add_u64 v[226:227], s[24:25], 0, v[130:131]
	s_mov_b32 m0, s52
	s_nop 0
	global_load_lds_dwordx4 v[226:227], off
	s_mov_b32 m0, s53
	s_nop 0
	global_load_lds_dwordx4 v[228:229], off
	s_waitcnt vmcnt(8)
	s_waitcnt lgkmcnt(0)
	s_barrier
	s_waitcnt lgkmcnt(0)
	v_mfma_f32_16x16x32_bf16 v[60:63], v[144:147], v[192:195], v[60:63]
	v_mfma_f32_16x16x32_bf16 v[56:59], v[158:161], v[192:195], v[56:59]
	v_mfma_f32_16x16x32_bf16 v[52:55], v[144:147], v[200:203], v[52:55]
	v_mfma_f32_16x16x32_bf16 v[48:51], v[158:161], v[200:203], v[48:51]
	v_mfma_f32_16x16x32_bf16 v[36:39], v[144:147], v[208:211], v[36:39]
	v_mfma_f32_16x16x32_bf16 v[32:35], v[158:161], v[208:211], v[32:35]
	v_mfma_f32_16x16x32_bf16 v[20:23], v[144:147], v[216:219], v[20:23]
	v_mfma_f32_16x16x32_bf16 v[16:19], v[158:161], v[216:219], v[16:19]
	v_mfma_f32_16x16x32_bf16 v[60:63], v[154:157], v[196:199], v[60:63]
	v_mfma_f32_16x16x32_bf16 v[56:59], v[162:165], v[196:199], v[56:59]
	v_mfma_f32_16x16x32_bf16 v[52:55], v[154:157], v[204:207], v[52:55]
	v_mfma_f32_16x16x32_bf16 v[48:51], v[162:165], v[204:207], v[48:51]
	v_mfma_f32_16x16x32_bf16 v[36:39], v[154:157], v[212:215], v[36:39]
	v_mfma_f32_16x16x32_bf16 v[32:35], v[162:165], v[212:215], v[32:35]
	v_mfma_f32_16x16x32_bf16 v[20:23], v[154:157], v[220:223], v[20:23]
	v_mfma_f32_16x16x32_bf16 v[16:19], v[162:165], v[220:223], v[16:19]
	v_mfma_f32_16x16x32_bf16 v[44:47], v[166:169], v[192:195], v[44:47]
	v_mfma_f32_16x16x32_bf16 v[40:43], v[174:177], v[192:195], v[40:43]
	v_mfma_f32_16x16x32_bf16 v[28:31], v[166:169], v[200:203], v[28:31]
	v_mfma_f32_16x16x32_bf16 v[24:27], v[174:177], v[200:203], v[24:27]
	v_mfma_f32_16x16x32_bf16 v[12:15], v[166:169], v[208:211], v[12:15]
	v_mfma_f32_16x16x32_bf16 v[8:11], v[174:177], v[208:211], v[8:11]
	v_mfma_f32_16x16x32_bf16 v[4:7], v[166:169], v[216:219], v[4:7]
	v_mfma_f32_16x16x32_bf16 v[0:3], v[174:177], v[216:219], v[0:3]
	v_mfma_f32_16x16x32_bf16 v[44:47], v[170:173], v[196:199], v[44:47]
	v_mfma_f32_16x16x32_bf16 v[40:43], v[178:181], v[196:199], v[40:43]
	v_mfma_f32_16x16x32_bf16 v[28:31], v[170:173], v[204:207], v[28:31]
	v_mfma_f32_16x16x32_bf16 v[24:27], v[178:181], v[204:207], v[24:27]
	v_mfma_f32_16x16x32_bf16 v[12:15], v[170:173], v[212:215], v[12:15]
	v_mfma_f32_16x16x32_bf16 v[8:11], v[178:181], v[212:215], v[8:11]
	v_mfma_f32_16x16x32_bf16 v[4:7], v[170:173], v[220:223], v[4:7]
	v_mfma_f32_16x16x32_bf16 v[0:3], v[178:181], v[220:223], v[0:3]
	s_barrier
	s_add_i32 s65, 0, 0x18000
	s_add_i32 s66, 0, 0x1c000
	v_add_u32_e32 v162, s65, v141
	v_add_u32_e32 v178, s65, v141
	ds_read_b128 v[144:147], v162
	ds_read_b128 v[154:157], v162 offset:1024
	ds_read_b128 v[158:161], v162 offset:2048
	ds_read_b128 v[162:165], v162 offset:3072
	ds_read_b128 v[166:169], v178 offset:4096
	ds_read_b128 v[170:173], v178 offset:5120
	ds_read_b128 v[174:177], v178 offset:6144
	ds_read_b128 v[178:181], v178 offset:7168
	s_add_u32 s24, s24, 0x80000
	s_addc_u32 s25, s25, 0
	s_mov_b32 m0, s54
	v_lshl_add_u64 v[230:231], s[24:25], 0, v[130:131]
	ds_read_b128 v[192:195], v143 offset:32768
	ds_read_b128 v[196:199], v143 offset:33792
	ds_read_b128 v[200:203], v143 offset:34816
	ds_read_b128 v[204:207], v143 offset:35840
	ds_read_b128 v[208:211], v143 offset:36864
	ds_read_b128 v[212:215], v143 offset:37888
	ds_read_b128 v[216:219], v143 offset:38912
	ds_read_b128 v[220:223], v143 offset:39936
	global_load_lds_dwordx4 v[230:231], off
	v_lshl_add_u64 v[230:231], s[24:25], 0, v[132:133]
	s_mov_b32 m0, s55
	s_nop 0
	global_load_lds_dwordx4 v[230:231], off
	s_waitcnt vmcnt(8)
	s_waitcnt lgkmcnt(0)
	s_barrier
	s_waitcnt lgkmcnt(0)
	v_mfma_f32_16x16x32_bf16 v[126:129], v[144:147], v[192:195], v[126:129]
	v_mfma_f32_16x16x32_bf16 v[122:125], v[158:161], v[192:195], v[122:125]
	v_mfma_f32_16x16x32_bf16 v[118:121], v[144:147], v[200:203], v[118:121]
	v_mfma_f32_16x16x32_bf16 v[114:117], v[158:161], v[200:203], v[114:117]
	v_mfma_f32_16x16x32_bf16 v[102:105], v[144:147], v[208:211], v[102:105]
	v_mfma_f32_16x16x32_bf16 v[98:101], v[158:161], v[208:211], v[98:101]
	v_mfma_f32_16x16x32_bf16 v[86:89], v[144:147], v[216:219], v[86:89]
	v_mfma_f32_16x16x32_bf16 v[82:85], v[158:161], v[216:219], v[82:85]
	v_mfma_f32_16x16x32_bf16 v[126:129], v[154:157], v[196:199], v[126:129]
	v_mfma_f32_16x16x32_bf16 v[122:125], v[162:165], v[196:199], v[122:125]
	v_mfma_f32_16x16x32_bf16 v[118:121], v[154:157], v[204:207], v[118:121]
	v_mfma_f32_16x16x32_bf16 v[114:117], v[162:165], v[204:207], v[114:117]
	v_mfma_f32_16x16x32_bf16 v[102:105], v[154:157], v[212:215], v[102:105]
	v_mfma_f32_16x16x32_bf16 v[98:101], v[162:165], v[212:215], v[98:101]
	v_mfma_f32_16x16x32_bf16 v[86:89], v[154:157], v[220:223], v[86:89]
	v_mfma_f32_16x16x32_bf16 v[82:85], v[162:165], v[220:223], v[82:85]
	v_mfma_f32_16x16x32_bf16 v[110:113], v[166:169], v[192:195], v[110:113]
	v_mfma_f32_16x16x32_bf16 v[106:109], v[174:177], v[192:195], v[106:109]
	v_mfma_f32_16x16x32_bf16 v[94:97], v[166:169], v[200:203], v[94:97]
	v_mfma_f32_16x16x32_bf16 v[90:93], v[174:177], v[200:203], v[90:93]
	v_mfma_f32_16x16x32_bf16 v[78:81], v[166:169], v[208:211], v[78:81]
	v_mfma_f32_16x16x32_bf16 v[74:77], v[174:177], v[208:211], v[74:77]
	v_mfma_f32_16x16x32_bf16 v[70:73], v[166:169], v[216:219], v[70:73]
	v_mfma_f32_16x16x32_bf16 v[66:69], v[174:177], v[216:219], v[66:69]
	v_mfma_f32_16x16x32_bf16 v[110:113], v[170:173], v[196:199], v[110:113]
	v_mfma_f32_16x16x32_bf16 v[106:109], v[178:181], v[196:199], v[106:109]
	v_mfma_f32_16x16x32_bf16 v[94:97], v[170:173], v[204:207], v[94:97]
	v_mfma_f32_16x16x32_bf16 v[90:93], v[178:181], v[204:207], v[90:93]
	v_mfma_f32_16x16x32_bf16 v[78:81], v[170:173], v[212:215], v[78:81]
	v_mfma_f32_16x16x32_bf16 v[74:77], v[178:181], v[212:215], v[74:77]
	v_mfma_f32_16x16x32_bf16 v[70:73], v[170:173], v[220:223], v[70:73]
	v_mfma_f32_16x16x32_bf16 v[66:69], v[178:181], v[220:223], v[66:69]
	s_barrier
	s_add_i32 s24, s65, s29
	v_lshl_add_u64 v[152:153], v[152:153], 0, s[30:31]
	s_mov_b32 m0, s24
	ds_read_b128 v[192:195], v143 offset:49152
	ds_read_b128 v[196:199], v143 offset:50176
	ds_read_b128 v[200:203], v143 offset:51200
	ds_read_b128 v[204:207], v143 offset:52224
	ds_read_b128 v[208:211], v143 offset:53248
	ds_read_b128 v[212:215], v143 offset:54272
	ds_read_b128 v[216:219], v143 offset:55296
	ds_read_b128 v[220:223], v143 offset:56320
	global_load_lds_dwordx4 v[152:153], off
	s_add_i32 m0, s24, 0x2000
	s_add_u32 s22, s22, 0x80080
	v_lshl_add_u64 v[152:153], v[224:225], 0, s[30:31]
	s_addc_u32 s23, s23, 0
	s_add_i32 s24, s66, s29
	global_load_lds_dwordx4 v[152:153], off
	v_lshl_add_u64 v[152:153], s[22:23], 0, v[64:65]
	s_mov_b32 m0, s24
	s_nop 0
	global_load_lds_dwordx4 v[152:153], off
	v_lshl_add_u64 v[152:153], s[22:23], 0, v[134:135]
	s_add_i32 m0, s24, 0x2000
	s_nop 0
	global_load_lds_dwordx4 v[152:153], off
	v_lshl_add_u64 v[152:153], v[226:227], 0, s[30:31]
	s_mov_b32 m0, s0
	s_nop 0
	global_load_lds_dwordx4 v[152:153], off
	v_lshl_add_u64 v[152:153], v[228:229], 0, s[30:31]
	s_mov_b32 m0, s56
	s_nop 0
	global_load_lds_dwordx4 v[152:153], off
	s_waitcnt vmcnt(8)
	s_waitcnt lgkmcnt(0)
	s_barrier
	s_waitcnt lgkmcnt(0)
	v_mfma_f32_16x16x32_bf16 v[60:63], v[144:147], v[192:195], v[60:63]
	v_mfma_f32_16x16x32_bf16 v[56:59], v[158:161], v[192:195], v[56:59]
	v_mfma_f32_16x16x32_bf16 v[52:55], v[144:147], v[200:203], v[52:55]
	v_mfma_f32_16x16x32_bf16 v[48:51], v[158:161], v[200:203], v[48:51]
	v_mfma_f32_16x16x32_bf16 v[36:39], v[144:147], v[208:211], v[36:39]
	v_mfma_f32_16x16x32_bf16 v[32:35], v[158:161], v[208:211], v[32:35]
	v_mfma_f32_16x16x32_bf16 v[20:23], v[144:147], v[216:219], v[20:23]
	v_mfma_f32_16x16x32_bf16 v[16:19], v[158:161], v[216:219], v[16:19]
	v_mfma_f32_16x16x32_bf16 v[60:63], v[154:157], v[196:199], v[60:63]
	v_mfma_f32_16x16x32_bf16 v[56:59], v[162:165], v[196:199], v[56:59]
	v_mfma_f32_16x16x32_bf16 v[52:55], v[154:157], v[204:207], v[52:55]
	v_mfma_f32_16x16x32_bf16 v[48:51], v[162:165], v[204:207], v[48:51]
	v_mfma_f32_16x16x32_bf16 v[36:39], v[154:157], v[212:215], v[36:39]
	v_mfma_f32_16x16x32_bf16 v[32:35], v[162:165], v[212:215], v[32:35]
	v_mfma_f32_16x16x32_bf16 v[20:23], v[154:157], v[220:223], v[20:23]
	v_mfma_f32_16x16x32_bf16 v[16:19], v[162:165], v[220:223], v[16:19]
	v_mfma_f32_16x16x32_bf16 v[44:47], v[166:169], v[192:195], v[44:47]
	v_mfma_f32_16x16x32_bf16 v[40:43], v[174:177], v[192:195], v[40:43]
	v_mfma_f32_16x16x32_bf16 v[28:31], v[166:169], v[200:203], v[28:31]
	v_mfma_f32_16x16x32_bf16 v[24:27], v[174:177], v[200:203], v[24:27]
	v_mfma_f32_16x16x32_bf16 v[12:15], v[166:169], v[208:211], v[12:15]
	v_mfma_f32_16x16x32_bf16 v[8:11], v[174:177], v[208:211], v[8:11]
	v_mfma_f32_16x16x32_bf16 v[4:7], v[166:169], v[216:219], v[4:7]
	v_mfma_f32_16x16x32_bf16 v[0:3], v[174:177], v[216:219], v[0:3]
	v_mfma_f32_16x16x32_bf16 v[44:47], v[170:173], v[196:199], v[44:47]
	v_mfma_f32_16x16x32_bf16 v[40:43], v[178:181], v[196:199], v[40:43]
	v_mfma_f32_16x16x32_bf16 v[28:31], v[170:173], v[204:207], v[28:31]
	v_mfma_f32_16x16x32_bf16 v[24:27], v[178:181], v[204:207], v[24:27]
	v_mfma_f32_16x16x32_bf16 v[12:15], v[170:173], v[212:215], v[12:15]
	v_mfma_f32_16x16x32_bf16 v[8:11], v[178:181], v[212:215], v[8:11]
	v_mfma_f32_16x16x32_bf16 v[4:7], v[170:173], v[220:223], v[4:7]
	v_mfma_f32_16x16x32_bf16 v[0:3], v[178:181], v[220:223], v[0:3]
	s_barrier
	s_add_i32 s47, s47, 2
	s_add_u32 s20, s20, 0x100
	s_addc_u32 s21, s21, 0
	s_add_u32 s61, s61, 0x100
	s_addc_u32 s64, s64, 0
	s_cmp_gt_u32 s47, 29
	s_cbranch_scc0 .LBB0_404
	s_and_b64 vcc, exec, s[8:9]
	s_cbranch_vccz .LBB0_407
	s_barrier
